# packed interleaved RWKV scan applied to both RWKV scan copies
# baseline (speedup 1.0000x reference)
; DI u16 f2bf(float f) { unsigned u = __float_as_uint(f); u += 0x7fffu + ((u >> 16) & 1u); return (u16)(u >> 16); }
; DI void rwkv_job(const Params& p, int l, int job, char* smem) {
;     ...
;   bf16x8 bw[4];
;   float bias;
;   {
;     const float* W = (mm == 0 ? p.rwkv_w_up : p.rwkv_a_up) + ((size_t)(l * 2 + d) * 64) * 512 + h * 64 + nt * 32 + r;
; #pragma unroll
;     for (int ks = 0; ks < 4; ++ks)
; #pragma unroll
;       for (int jj = 0; jj < 8; ++jj) bw[ks][jj] = (short)f2bf(W[(size_t)(16 * ks + 8 * hh + jj) * 512]);
;     bias = (mm == 0 ? p.rwkv_w0 : p.rwkv_a0)[(l * 2 + d) * 512 + h * 64 + nt * 32 + r];
;   }
;   const int rp = lane >> 4, kg = lane & 15;
;   float SA[4], SB[4];
; #pragma unroll
;   for (int i = 0; i < 4; ++i) { SA[i] = 0.f; SB[i] = 0.f; }
;   const int myrow = 32 * half + 8 * wave + 2 * rp;
;   u16* ysb = p.R2 + (size_t)d * NTOK * 512 + (size_t)b * TPB * 512 + h * 64 + myrow;
;   u32x4 q_rp, q_rm, q_rn, q_kp, q_km, q_kn, q_vp, q_vm, q_vn, q_wp, q_wm, q_wn, q_ap, q_am, q_an;
;   bool hp, hn;
;   int ptok;
.LBB0_653:
	s_or_b64 exec, exec, s[4:5]
	s_mul_i32 s10, s2, 0x1100
	s_and_b32 s2, s37, 1
	s_lshl_b32 s4, s2, 5
	v_lshl_add_u32 v3, v3, 3, s4
	s_mul_hi_i32 s11, s75, 0x8800
	s_mul_i32 s12, s75, 0x8800
	s_mul_hi_i32 s4, s75, 0x2200000
	s_mul_i32 s75, s75, 0x2200000
	s_add_u32 s5, s64, s75
	s_addc_u32 s4, s65, s4
	s_lshl_b32 s13, s10, 10
	s_add_u32 s5, s5, s13
	v_and_b32_e32 v136, 15, v2
	v_lshrrev_b32_e32 v2, 3, v2
	s_addc_u32 s13, s4, 0
	s_lshl_b32 s4, s36, 1
	v_and_or_b32 v126, v2, 6, v3
	s_add_u32 s4, s5, s4
	s_addc_u32 s5, s13, 0
	v_ashrrev_i32_e32 v127, 31, v126
	v_lshl_add_u64 v[128:129], v[126:127], 1, s[4:5]
	s_movk_i32 s4, 0x600
	v_mul_lo_u32 v2, v134, s4
	v_lshlrev_b32_e32 v127, 2, v89
	s_waitcnt vmcnt(25)
	v_bfe_u32 v4, v25, 16, 1
	v_bfe_u32 v5, v24, 16, 1
	v_bfe_u32 v6, v19, 16, 1
	v_bfe_u32 v7, v18, 16, 1
	v_bfe_u32 v8, v26, 16, 1
	v_bfe_u32 v9, v20, 16, 1
	v_bfe_u32 v90, v28, 16, 1
	v_or_b32_e32 v137, v127, v2
	v_mov_b32_e32 v2, 0xd200
	v_mov_b32_e32 v3, 0xc000
	v_add3_u32 v28, v28, v90, s38
	v_add3_u32 v20, v20, v9, s38
	v_add3_u32 v26, v26, v8, s38
	v_add3_u32 v18, v18, v7, s38
	v_add3_u32 v19, v19, v6, s38
	v_add3_u32 v24, v24, v5, s38
	v_add3_u32 v25, v25, v4, s38
	s_waitcnt vmcnt(21)
	v_bfe_u32 v4, v83, 16, 1
	v_bfe_u32 v5, v15, 16, 1
	v_bfe_u32 v6, v21, 16, 1
	v_bfe_u32 v7, v14, 16, 1
	v_bfe_u32 v8, v12, 16, 1
	v_bfe_u32 v9, v11, 16, 1
	v_bfe_u32 v90, v22, 16, 1
	s_movk_i32 s4, 0x90
	v_cndmask_b32_e64 v2, v2, v3, s[8:9]
	v_bfe_u32 v91, v27, 16, 1
	v_add3_u32 v22, v22, v90, s38
	v_add3_u32 v90, v11, v9, s38
	v_add3_u32 v108, v12, v8, s38
	v_add3_u32 v109, v14, v7, s38
	v_add3_u32 v21, v21, v6, s38
	v_add3_u32 v110, v15, v5, s38
	v_add3_u32 v83, v83, v4, s38
	s_waitcnt vmcnt(15)
	v_bfe_u32 v4, v30, 16, 1
	v_bfe_u32 v5, v29, 16, 1
	s_waitcnt vmcnt(13)
	v_bfe_u32 v6, v87, 16, 1
	v_bfe_u32 v7, v77, 16, 1
	v_bfe_u32 v8, v76, 16, 1
	v_bfe_u32 v9, v31, 16, 1
	v_bfe_u32 v11, v17, 16, 1
	v_bfe_u32 v12, v78, 16, 1
	v_mad_u32_u24 v131, v1, s4, v2
	v_cndmask_b32_e64 v2, v228, v233, s[8:9]
	s_add_u32 s36, s12, s10
	v_readlane_b32 s12, v254, 59
	v_add3_u32 v27, v27, v91, s38
	v_bfe_u32 v91, v13, 16, 1
	v_add3_u32 v111, v78, v12, s38
	v_add3_u32 v17, v17, v11, s38
	v_add3_u32 v31, v31, v9, s38
	v_add3_u32 v112, v76, v8, s38
	v_add3_u32 v113, v77, v7, s38
	v_add3_u32 v114, v87, v6, s38
	v_add3_u32 v29, v29, v5, s38
	v_add3_u32 v30, v30, v4, s38
	s_waitcnt vmcnt(6)
	v_bfe_u32 v4, v82, 16, 1
	v_bfe_u32 v5, v81, 16, 1
	v_bfe_u32 v6, v80, 16, 1
	v_bfe_u32 v7, v86, 16, 1
	v_bfe_u32 v8, v85, 16, 1
	v_bfe_u32 v9, v84, 16, 1
	v_bfe_u32 v11, v79, 16, 1
	v_bfe_u32 v12, v23, 16, 1
	v_mul_lo_u32 v125, v134, s4
	v_lshl_or_b32 v2, v10, 2, v2
	s_addc_u32 s37, s11, 0
	s_lshl_b32 s4, s74, 2
	v_readlane_b32 s16, v254, 63
	v_add3_u32 v91, v13, v91, s38
	v_add3_u32 v23, v23, v12, s38
	v_add3_u32 v115, v79, v11, s38
	v_add3_u32 v116, v84, v9, s38
	v_add3_u32 v117, v85, v8, s38
	v_add3_u32 v118, v86, v7, s38
	v_add3_u32 v119, v80, v6, s38
	v_add3_u32 v121, v81, v5, s38
	v_add3_u32 v123, v82, v4, s38
	v_lshlrev_b32_e32 v130, 4, v88
	v_lshlrev_b32_e32 v132, 4, v16
	v_lshl_add_u32 v133, v1, 2, v2
	v_or_b32_e32 v1, s2, v88
	v_lshlrev_b32_e32 v139, 4, v136
	v_lshlrev_b32_e32 v140, 2, v126
	v_mul_u32_u24_e32 v16, 0x1800, v16
	v_readlane_b32 s17, v255, 0
	s_add_u32 s92, s16, s4
	s_mov_b32 s2, 0
	v_cmp_eq_u32_e64 s[8:9], 0, v1
	v_lshlrev_b32_e32 v138, 2, v136
	s_waitcnt vmcnt(5)
	v_mov_b32_e32 v1, v0
	v_mov_b32_e32 v2, v0
	v_mov_b32_e32 v3, v0
	v_mov_b32_e32 v4, v0
	v_mov_b32_e32 v5, v0
	v_mov_b32_e32 v6, v0
	v_mov_b32_e32 v7, v0
	v_mov_b32_e32 v8, v0
	v_mov_b32_e32 v9, v0
	v_mov_b32_e32 v10, v0
	v_mov_b32_e32 v11, v0
	v_mov_b32_e32 v12, v0
	v_mov_b32_e32 v13, v0
	v_mov_b32_e32 v14, v0
	v_mov_b32_e32 v15, v0
	v_perm_b32 v79, v25, v24, s87
	v_perm_b32 v78, v19, v18, s87
	v_perm_b32 v77, v26, v20, s87
	v_perm_b32 v76, v28, v27, s87
	v_perm_b32 v83, v83, v110, s87
	v_perm_b32 v82, v21, v109, s87
	v_perm_b32 v81, v108, v90, s87
	v_perm_b32 v80, v22, v91, s87
	v_perm_b32 v87, v30, v29, s87
	v_perm_b32 v86, v114, v113, s87
	v_perm_b32 v85, v112, v31, s87
	v_perm_b32 v84, v17, v111, s87
	v_perm_b32 v91, v123, v121, s87
	v_perm_b32 v90, v119, v118, s87
	v_perm_b32 v89, v117, v116, s87
	v_perm_b32 v88, v115, v23, s87
	s_addc_u32 s93, s17, 0
	v_and_b32_e32 v141, 3, v136
	v_lshrrev_b32_e32 v142, 2, v136
	v_lshl_add_u32 v141, v141, 2, v142
	v_sub_u32_e32 v142, 0x120b, v141
	v_add_u32_e32 v141, -12, v141
	v_or_b32_e32 v143, 0x600, v139
	v_add_u32_e32 v148, 0xb00, v140
	v_add_u32_e32 v149, v125, v130
	v_add_u32_e32 v150, v131, v132
	v_add_u32_e32 v151, v133, v16
	v_mov_b32_e32 v152, 0
	v_mov_b32_e32 v153, 0
	v_mov_b32_e32 v154, 0
	v_mov_b32_e32 v155, 0
	v_mov_b32_e32 v156, 0
	v_mov_b32_e32 v157, 0
	v_mov_b32_e32 v158, 0
	v_mov_b32_e32 v198, 0
	v_mov_b32_e32 v199, 0
	v_mov_b32_e32 v200, 0
	v_mov_b32_e32 v201, 0
	v_mov_b32_e32 v202, 0
	v_mov_b32_e32 v203, 0
	v_mov_b32_e32 v204, 0
	v_mov_b32_e32 v205, 0
	s_waitcnt lgkmcnt(0)
	s_barrier
	v_readlane_b32 s13, v254, 60
	v_readlane_b32 s14, v254, 61
	v_readlane_b32 s15, v254, 62
	v_readlane_b32 s18, v255, 1
	v_readlane_b32 s19, v255, 2
	v_readlane_b32 s20, v255, 3
	v_readlane_b32 s21, v255, 4
	v_readlane_b32 s22, v255, 5
	v_readlane_b32 s23, v255, 6
	v_readlane_b32 s24, v255, 7
	v_readlane_b32 s25, v255, 8
	v_readlane_b32 s26, v255, 9
	v_readlane_b32 s27, v255, 10
	s_branch .LBB0_655

; DI void rwkv_job(const Params& p, int l, int job, char* smem) {
;     ...
;       RW_LDOPS(A, 0)
; #pragma unroll 1
;       for (int st = 0; st < RC; st += 4) {
;         RW_LDOPS(B, st + 1)
;         RW_STEP(A, st, 0)
;         RW_LDOPS(A, st + 2)
;         RW_STEP(B, st + 1, 0)
;         RW_LDOPS(B, st + 3)
;         RW_STEP(A, st + 2, 0)
;         const int sn = st + 4 < RC ? st + 4 : RC - 1;
;         RW_LDOPS(A, sn)
;         RW_STEP(B, st + 3, 1)
.LBB0_685:
	s_waitcnt lgkmcnt(7)
	v_pk_mul_f32 v[182:183], v[198:199], v[108:109]
	v_pk_mul_f32 v[184:185], v[202:203], v[108:109]
	s_cmp_gt_u32 s2, 27
	v_pk_fma_f32 v[182:183], v[200:201], v[110:111], v[182:183]
	v_pk_fma_f32 v[184:185], v[204:205], v[110:111], v[184:185]
	s_cselect_b64 s[10:11], -1, 0
	v_add_f32_e32 v180, v182, v183
	v_add_f32_e32 v181, v184, v185
	v_pk_mul_f32 v[208:209], v[112:113], v[24:25] op_sel_hi:[0,1]
	v_add_f32_dpp v180, v180, v180 quad_perm:[1,0,3,2] row_mask:0xf bank_mask:0xf bound_ctrl:1
	v_add_f32_dpp v181, v181, v181 quad_perm:[1,0,3,2] row_mask:0xf bank_mask:0xf bound_ctrl:1
	v_pk_mul_f32 v[210:211], v[112:113], v[24:25] op_sel:[1,0] op_sel_hi:[1,1]
	v_add_f32_dpp v180, v180, v180 quad_perm:[2,3,0,1] row_mask:0xf bank_mask:0xf bound_ctrl:1
	v_add_f32_dpp v181, v181, v181 quad_perm:[2,3,0,1] row_mask:0xf bank_mask:0xf bound_ctrl:1
	v_pk_mul_f32 v[130:131], v[112:113], v[26:27] op_sel_hi:[0,1]
	v_add_f32_dpp v180, v180, v180 row_half_mirror row_mask:0xf bank_mask:0xf bound_ctrl:1
	v_add_f32_dpp v181, v181, v181 row_half_mirror row_mask:0xf bank_mask:0xf bound_ctrl:1
	v_pk_mul_f32 v[132:133], v[112:113], v[26:27] op_sel:[1,0] op_sel_hi:[1,1]
	v_add_f32_dpp v180, v180, v180 row_mirror row_mask:0xf bank_mask:0xf bound_ctrl:1
	v_add_f32_dpp v181, v181, v181 row_mirror row_mask:0xf bank_mask:0xf bound_ctrl:1
	v_pk_fma_f32 v[208:209], v[180:181], v[28:29], v[208:209] op_sel_hi:[0,1,1]
	v_pk_fma_f32 v[210:211], v[180:181], v[28:29], v[210:211] op_sel:[1,0,0] op_sel_hi:[1,1,1]
	v_pk_fma_f32 v[130:131], v[180:181], v[30:31], v[130:131] op_sel_hi:[0,1,1]
	v_pk_fma_f32 v[132:133], v[180:181], v[30:31], v[132:133] op_sel:[1,0,0] op_sel_hi:[1,1,1]
	v_pk_fma_f32 v[198:199], v[198:199], v[20:21], v[208:209]
	v_pk_fma_f32 v[202:203], v[202:203], v[20:21], v[210:211]
	v_pk_fma_f32 v[200:201], v[200:201], v[22:23], v[130:131]
	v_pk_fma_f32 v[204:205], v[204:205], v[22:23], v[132:133]
	ds_read_b128 v[108:111], v115 offset:2304
	ds_read_b64 v[112:113], v114 offset:1536
	ds_read_b128 v[24:27], v115 offset:2048
	ds_read_b128 v[28:31], v115 offset:2560
	ds_read_b128 v[20:23], v115 offset:1792
	s_waitcnt lgkmcnt(11)
	s_waitcnt lgkmcnt(6)
	v_pk_mul_f32 v[182:183], v[198:199], v[168:169]
	v_pk_mul_f32 v[184:185], v[202:203], v[168:169]
	v_pk_mul_f32 v[186:187], v[198:199], v[16:17]
	v_pk_mul_f32 v[188:189], v[202:203], v[16:17]
	v_pk_fma_f32 v[182:183], v[200:201], v[170:171], v[182:183]
	v_pk_fma_f32 v[184:185], v[204:205], v[170:171], v[184:185]
	v_pk_fma_f32 v[186:187], v[200:201], v[18:19], v[186:187]
	v_pk_fma_f32 v[188:189], v[204:205], v[18:19], v[188:189]
	v_add_f32_e32 v180, v182, v183
	v_add_f32_e32 v181, v184, v185
	v_add_f32_e32 v146, v186, v187
	v_add_f32_e32 v147, v188, v189
	ds_read_b128 v[16:19], v115 offset:1536
	v_pk_mul_f32 v[208:209], v[172:173], v[164:165] op_sel_hi:[0,1]
	v_add_f32_dpp v180, v180, v180 quad_perm:[1,0,3,2] row_mask:0xf bank_mask:0xf bound_ctrl:1
	v_add_f32_dpp v181, v181, v181 quad_perm:[1,0,3,2] row_mask:0xf bank_mask:0xf bound_ctrl:1
	v_pk_mul_f32 v[210:211], v[172:173], v[164:165] op_sel:[1,0] op_sel_hi:[1,1]
	v_add_f32_dpp v180, v180, v180 quad_perm:[2,3,0,1] row_mask:0xf bank_mask:0xf bound_ctrl:1
	v_add_f32_dpp v181, v181, v181 quad_perm:[2,3,0,1] row_mask:0xf bank_mask:0xf bound_ctrl:1
	v_pk_mul_f32 v[130:131], v[172:173], v[166:167] op_sel_hi:[0,1]
	v_add_f32_dpp v180, v180, v180 row_half_mirror row_mask:0xf bank_mask:0xf bound_ctrl:1
	v_add_f32_dpp v181, v181, v181 row_half_mirror row_mask:0xf bank_mask:0xf bound_ctrl:1
	v_pk_mul_f32 v[132:133], v[172:173], v[166:167] op_sel:[1,0] op_sel_hi:[1,1]
	v_add_f32_dpp v180, v180, v180 row_mirror row_mask:0xf bank_mask:0xf bound_ctrl:1
	v_add_f32_dpp v181, v181, v181 row_mirror row_mask:0xf bank_mask:0xf bound_ctrl:1
	v_pk_fma_f32 v[208:209], v[180:181], v[176:177], v[208:209] op_sel_hi:[0,1,1]
	v_pk_fma_f32 v[210:211], v[180:181], v[176:177], v[210:211] op_sel:[1,0,0] op_sel_hi:[1,1,1]
	v_pk_fma_f32 v[130:131], v[180:181], v[178:179], v[130:131] op_sel_hi:[0,1,1]
	v_pk_fma_f32 v[132:133], v[180:181], v[178:179], v[132:133] op_sel:[1,0,0] op_sel_hi:[1,1,1]
	v_pk_fma_f32 v[198:199], v[198:199], v[160:161], v[208:209]
	v_pk_fma_f32 v[202:203], v[202:203], v[160:161], v[210:211]
	v_pk_fma_f32 v[200:201], v[200:201], v[162:163], v[130:131]
	v_pk_fma_f32 v[204:205], v[204:205], v[162:163], v[132:133]
	ds_read_b128 v[168:171], v115 offset:3840
	ds_read_b64 v[172:173], v114 offset:3072
	ds_read_b128 v[164:167], v115 offset:3584
	ds_read_b128 v[176:179], v115 offset:4096
	ds_read_b128 v[160:163], v115 offset:3328
	s_waitcnt lgkmcnt(11)
	s_waitcnt lgkmcnt(6)
; DI void rwkv_job(const Params& p, int l, int job, char* smem) {
;     ...
;         RW_STEP(B, st + 1, 0)
;         RW_LDOPS(B, st + 3)
;         RW_STEP(A, st + 2, 0)
;         const int sn = st + 4 < RC ? st + 4 : RC - 1;
;         RW_LDOPS(A, sn)
;         RW_STEP(B, st + 3, 1)
;       }
	v_pk_mul_f32 v[182:183], v[198:199], v[108:109]
	v_pk_mul_f32 v[184:185], v[202:203], v[108:109]
	v_pk_mul_f32 v[186:187], v[198:199], v[212:213]
	v_pk_mul_f32 v[188:189], v[202:203], v[212:213]
	v_pk_fma_f32 v[182:183], v[200:201], v[110:111], v[182:183]
	v_pk_fma_f32 v[184:185], v[204:205], v[110:111], v[184:185]
	v_pk_fma_f32 v[186:187], v[200:201], v[214:215], v[186:187]
	v_pk_fma_f32 v[188:189], v[204:205], v[214:215], v[188:189]
	v_add_f32_e32 v180, v182, v183
	v_add_f32_e32 v181, v184, v185
	v_add_f32_e32 v190, v186, v187
	v_add_f32_e32 v191, v188, v189
	ds_read_b128 v[212:215], v115 offset:3072
	v_pk_mul_f32 v[208:209], v[112:113], v[24:25] op_sel_hi:[0,1]
	v_add_f32_dpp v180, v180, v180 quad_perm:[1,0,3,2] row_mask:0xf bank_mask:0xf bound_ctrl:1
	v_add_f32_dpp v181, v181, v181 quad_perm:[1,0,3,2] row_mask:0xf bank_mask:0xf bound_ctrl:1
	v_pk_mul_f32 v[210:211], v[112:113], v[24:25] op_sel:[1,0] op_sel_hi:[1,1]
	v_add_f32_dpp v180, v180, v180 quad_perm:[2,3,0,1] row_mask:0xf bank_mask:0xf bound_ctrl:1
	v_add_f32_dpp v181, v181, v181 quad_perm:[2,3,0,1] row_mask:0xf bank_mask:0xf bound_ctrl:1
	v_pk_mul_f32 v[130:131], v[112:113], v[26:27] op_sel_hi:[0,1]
	v_add_f32_dpp v180, v180, v180 row_half_mirror row_mask:0xf bank_mask:0xf bound_ctrl:1
	v_add_f32_dpp v181, v181, v181 row_half_mirror row_mask:0xf bank_mask:0xf bound_ctrl:1
	v_pk_mul_f32 v[132:133], v[112:113], v[26:27] op_sel:[1,0] op_sel_hi:[1,1]
	v_add_f32_dpp v180, v180, v180 row_mirror row_mask:0xf bank_mask:0xf bound_ctrl:1
	v_add_f32_dpp v181, v181, v181 row_mirror row_mask:0xf bank_mask:0xf bound_ctrl:1
	v_pk_fma_f32 v[208:209], v[180:181], v[28:29], v[208:209] op_sel_hi:[0,1,1]
	v_pk_fma_f32 v[210:211], v[180:181], v[28:29], v[210:211] op_sel:[1,0,0] op_sel_hi:[1,1,1]
	v_pk_fma_f32 v[130:131], v[180:181], v[30:31], v[130:131] op_sel_hi:[0,1,1]
	v_pk_fma_f32 v[132:133], v[180:181], v[30:31], v[132:133] op_sel:[1,0,0] op_sel_hi:[1,1,1]
	v_pk_fma_f32 v[198:199], v[198:199], v[20:21], v[208:209]
	v_pk_fma_f32 v[202:203], v[202:203], v[20:21], v[210:211]
	v_pk_fma_f32 v[200:201], v[200:201], v[22:23], v[130:131]
	v_pk_fma_f32 v[204:205], v[204:205], v[22:23], v[132:133]
	ds_read_b128 v[108:111], v115 offset:5376
	ds_read_b64 v[112:113], v114 offset:4608
	ds_read_b128 v[24:27], v115 offset:5120
	ds_read_b128 v[28:31], v115 offset:5632
	ds_read_b128 v[20:23], v115 offset:4864
	s_waitcnt lgkmcnt(11)
	s_waitcnt lgkmcnt(6)
	v_pk_mul_f32 v[182:183], v[198:199], v[168:169]
	v_pk_mul_f32 v[184:185], v[202:203], v[168:169]
	v_pk_mul_f32 v[186:187], v[198:199], v[16:17]
	v_pk_mul_f32 v[188:189], v[202:203], v[16:17]
	v_pk_fma_f32 v[182:183], v[200:201], v[170:171], v[182:183]
	v_pk_fma_f32 v[184:185], v[204:205], v[170:171], v[184:185]
	v_pk_fma_f32 v[186:187], v[200:201], v[18:19], v[186:187]
	v_pk_fma_f32 v[188:189], v[204:205], v[18:19], v[188:189]
	v_add_f32_e32 v180, v182, v183
	v_add_f32_e32 v181, v184, v185
	v_add_f32_e32 v192, v186, v187
	v_add_f32_e32 v193, v188, v189
	ds_read_b128 v[16:19], v115 offset:4608
	v_pk_mul_f32 v[208:209], v[172:173], v[164:165] op_sel_hi:[0,1]
	v_add_f32_dpp v180, v180, v180 quad_perm:[1,0,3,2] row_mask:0xf bank_mask:0xf bound_ctrl:1
	v_add_f32_dpp v181, v181, v181 quad_perm:[1,0,3,2] row_mask:0xf bank_mask:0xf bound_ctrl:1
	v_pk_mul_f32 v[210:211], v[172:173], v[164:165] op_sel:[1,0] op_sel_hi:[1,1]
	v_add_f32_dpp v180, v180, v180 quad_perm:[2,3,0,1] row_mask:0xf bank_mask:0xf bound_ctrl:1
	v_add_f32_dpp v181, v181, v181 quad_perm:[2,3,0,1] row_mask:0xf bank_mask:0xf bound_ctrl:1
	v_pk_mul_f32 v[130:131], v[172:173], v[166:167] op_sel_hi:[0,1]
	v_add_f32_dpp v180, v180, v180 row_half_mirror row_mask:0xf bank_mask:0xf bound_ctrl:1
	v_add_f32_dpp v181, v181, v181 row_half_mirror row_mask:0xf bank_mask:0xf bound_ctrl:1
	v_pk_mul_f32 v[132:133], v[172:173], v[166:167] op_sel:[1,0] op_sel_hi:[1,1]
	v_add_f32_dpp v180, v180, v180 row_mirror row_mask:0xf bank_mask:0xf bound_ctrl:1
	v_add_f32_dpp v181, v181, v181 row_mirror row_mask:0xf bank_mask:0xf bound_ctrl:1
	v_pk_fma_f32 v[208:209], v[180:181], v[176:177], v[208:209] op_sel_hi:[0,1,1]
	v_pk_fma_f32 v[210:211], v[180:181], v[176:177], v[210:211] op_sel:[1,0,0] op_sel_hi:[1,1,1]
	v_pk_fma_f32 v[130:131], v[180:181], v[178:179], v[130:131] op_sel_hi:[0,1,1]
	v_pk_fma_f32 v[132:133], v[180:181], v[178:179], v[132:133] op_sel:[1,0,0] op_sel_hi:[1,1,1]
	v_pk_fma_f32 v[198:199], v[198:199], v[160:161], v[208:209]
	v_pk_fma_f32 v[202:203], v[202:203], v[160:161], v[210:211]
	v_pk_fma_f32 v[200:201], v[200:201], v[162:163], v[130:131]
	v_pk_fma_f32 v[204:205], v[204:205], v[162:163], v[132:133]
	ds_read_b128 v[168:171], v115 offset:6912
	ds_read_b64 v[172:173], v114 offset:6144
	ds_read_b128 v[164:167], v115 offset:6656
	ds_read_b128 v[176:179], v115 offset:7168
	ds_read_b128 v[160:163], v115 offset:6400
	s_waitcnt lgkmcnt(11)
	v_pk_mul_f32 v[186:187], v[198:199], v[212:213]
	v_pk_mul_f32 v[188:189], v[202:203], v[212:213]
	s_bfe_u32 s75, s2, 0x20002
	v_pk_fma_f32 v[186:187], v[200:201], v[214:215], v[186:187]
	v_pk_fma_f32 v[188:189], v[204:205], v[214:215], v[188:189]
	v_add_f32_dpp v146, v146, v146 row_ror:8 row_mask:0xf bank_mask:0x3 bound_ctrl:1
	v_add_f32_e32 v206, v186, v187
	v_add_f32_e32 v207, v188, v189
	ds_read_b128 v[212:215], v115 offset:6144
	v_add_f32_dpp v147, v147, v147 row_ror:8 row_mask:0xf bank_mask:0x3 bound_ctrl:1
	v_add_f32_dpp v190, v190, v190 row_ror:8 row_mask:0xf bank_mask:0x3 bound_ctrl:1
	v_add_f32_dpp v191, v191, v191 row_ror:8 row_mask:0xf bank_mask:0x3 bound_ctrl:1
	v_add_f32_dpp v146, v192, v192 row_ror:8 row_mask:0xf bank_mask:0xc bound_ctrl:1
	v_add_f32_dpp v147, v193, v193 row_ror:8 row_mask:0xf bank_mask:0xc bound_ctrl:1
	v_add_f32_dpp v190, v206, v206 row_ror:8 row_mask:0xf bank_mask:0xc bound_ctrl:1
	v_add_f32_dpp v191, v207, v207 row_ror:8 row_mask:0xf bank_mask:0xc bound_ctrl:1
	v_add_f32_dpp v146, v146, v146 row_half_mirror row_mask:0xf bank_mask:0x5 bound_ctrl:1
	v_add_f32_dpp v147, v147, v147 row_half_mirror row_mask:0xf bank_mask:0x5 bound_ctrl:1
	v_add_f32_dpp v146, v190, v190 row_half_mirror row_mask:0xf bank_mask:0xa bound_ctrl:1
	v_add_f32_dpp v147, v191, v191 row_half_mirror row_mask:0xf bank_mask:0xa bound_ctrl:1
	s_lshl_b32 s12, 0x11111111, s75
	v_add_f32_dpp v146, v146, v146 quad_perm:[1,0,3,2] row_mask:0xf bank_mask:0xf bound_ctrl:1
	v_add_f32_dpp v147, v147, v147 quad_perm:[1,0,3,2] row_mask:0xf bank_mask:0xf bound_ctrl:1
	s_mov_b32 s13, s12
	v_add_f32_dpp v146, v146, v146 quad_perm:[2,3,0,1] row_mask:0xf bank_mask:0xf bound_ctrl:1
	v_add_f32_dpp v147, v147, v147 quad_perm:[2,3,0,1] row_mask:0xf bank_mask:0xf bound_ctrl:1
	s_and_b32 s5, s2, 12
	v_cndmask_b32_e64 v117, v117, v146, s[12:13]
	v_cndmask_b32_e64 v118, v118, v147, s[12:13]
	s_cmp_lg_u32 s5, 12
	s_cbranch_scc1 .LBB0_684
	v_add_u32_e32 v119, s2, v141
	v_add_u32_e32 v121, 0xffffef00, v116
	v_cndmask_b32_e64 v121, v121, v119, s[6:7]
	v_cndmask_b32_e64 v123, v116, v119, s[6:7]
	v_cmp_gt_i32_e32 vcc, s33, v119
	v_cvt_pk_bf16_f32 v119, v117, v118
	s_nop 0
	v_cndmask_b32_e32 v130, v123, v121, vcc
	v_ashrrev_i32_e32 v131, 31, v130
	v_lshlrev_b64 v[130:131], 10, v[130:131]
	v_lshl_add_u64 v[130:131], v[128:129], 0, v[130:131]
	global_store_dword v[130:131], v119, off
	s_branch .LBB0_684
